# rows phase: SLP-gathered packed ops turned into single ops on the original registers (96 gather moves removed), invariant spilled-scalar reloads hoisted to spare SGPRs
# speedup vs baseline: 1.0129x; 1.0129x over previous
.LBB0_449:
	v_and_b32_e32 v39, 32, v34
	v_cmp_eq_u32_e64 s[40:41], 0, v39
	v_and_b32_e32 v39, 16, v34
	v_lshrrev_b32_e32 v42, 1, v35
	v_readlane_b32 s2, v251, 14
	v_cmp_eq_u32_e64 s[42:43], 0, v39
	v_cmp_eq_u32_e64 s[46:47], 0, v38
	v_and_b32_e32 v38, 16, v42
	v_mov_b32_e32 v39, v9
	v_readlane_b32 s3, v251, 15
	s_add_i32 s1, 0, 0x1c000
	v_add_u32_e32 v101, s1, v8
	v_lshl_add_u64 v[38:39], s[2:3], 0, v[38:39]
	v_readlane_b32 s1, v253, 26
	v_readlane_b32 s2, v251, 59
	v_mov_b32_e32 v37, v9
	s_mul_i32 s4, s36, 24
	v_add_u32_e32 v102, s1, v8
	v_readlane_b32 s3, v251, 60
	s_ashr_i32 s1, s0, 31
	s_lshl_b32 s58, s36, 4
	s_lshl_b32 s59, s36, 5
	v_lshl_add_u64 v[66:67], s[2:3], 0, v[36:37]
	s_ashr_i32 s5, s4, 31
	s_lshl_b64 s[2:3], s[0:1], 5
	v_and_b32_e32 v40, 8, v34
	s_add_u32 s2, s2, 0x1e500000
	v_cmp_eq_u32_e64 s[44:45], 0, v40
	v_and_b32_e32 v40, 8, v42
	v_mov_b32_e32 v41, v9
	s_addc_u32 s3, s3, 0
	v_lshrrev_b32_e32 v34, 1, v34
	v_lshl_add_u64 v[38:39], v[38:39], 0, v[40:41]
	v_and_b32_e32 v42, 4, v42
	v_mov_b32_e32 v43, v9
	v_and_or_b32 v34, v34, 16, s2
	v_mov_b32_e32 v69, s3
	s_lshl_b64 s[2:3], s[0:1], 11
	v_lshl_add_u64 v[62:63], s[70:71], 0, v[36:37]
	v_add_u32_e32 v100, 0, v8
	v_lshl_add_u64 v[64:65], v[38:39], 0, v[42:43]
	v_or3_b32 v68, v34, v40, v42
	s_lshl_b64 s[6:7], s[4:5], 5
	v_lshl_or_b32 v70, v35, 3, s2
	v_mov_b32_e32 v71, s3
	s_lshl_b64 s[34:35], s[4:5], 11
	s_mov_b64 s[50:51], s[0:1]
	v_xor_b32_e32 v244, 1, v220
	v_xor_b32_e32 v245, 2, v220
	v_xor_b32_e32 v246, 4, v220
	v_xor_b32_e32 v247, 8, v220
	v_xor_b32_e32 v248, 16, v220
	v_xor_b32_e32 v249, 32, v220
	v_lshlrev_b32_e32 v244, 2, v244
	v_lshlrev_b32_e32 v245, 2, v245
	v_lshlrev_b32_e32 v246, 2, v246
	v_lshlrev_b32_e32 v247, 2, v247
	v_lshlrev_b32_e32 v248, 2, v248
	v_lshlrev_b32_e32 v249, 2, v249
	v_readlane_b32 s78, v254, 57
	v_readlane_b32 s79, v254, 56
	v_readlane_b32 s80, v254, 18
	v_readlane_b32 s81, v254, 55
	v_readlane_b32 s82, v254, 54
	v_readlane_b32 s83, v251, 10
	v_readlane_b32 s84, v251, 11
	v_readlane_b32 s85, v252, 8
	v_readlane_b32 s86, v252, 7
	v_readlane_b32 s87, v251, 12
	v_readlane_b32 s88, v251, 13
	v_readlane_b32 s89, v254, 27
	v_readlane_b32 s90, v254, 28
	s_branch .LBB0_452

.LBB0_452:
	s_add_u32 s52, s58, s50
	s_cmp_lt_i32 s52, s26
	s_cselect_b64 s[54:55], -1, 0
	s_and_b64 s[2:3], s[54:55], exec
	s_cselect_b32 s24, s52, s0
	s_cmpk_gt_i32 s24, 0x7fff
	s_mov_b64 s[28:29], -1
	s_cbranch_scc0 .LBB0_454
	s_add_i32 s26, s24, 0xffff8000
	s_lshl_b64 s[2:3], s[26:27], 12
	s_mov_b32 s1, s78
	s_add_u32 s18, s1, s2
	s_mov_b32 s1, s79
	s_mov_b32 s26, s80
	s_addc_u32 s19, s1, s3
	s_mov_b32 s25, s27
	s_mov_b64 s[28:29], 0
.LBB0_454:
	s_andn2_b64 vcc, exec, s[28:29]
	s_cbranch_vccnz .LBB0_456
	s_ashr_i32 s25, s24, 31
	s_lshl_b64 s[2:3], s[24:25], 12
	s_mov_b32 s1, s81
	s_add_u32 s18, s1, s2
	s_mov_b32 s1, s82
	s_addc_u32 s19, s1, s3

.LBB0_463:
	s_waitcnt vmcnt(11)
	v_and_b32_e32 v121, 0xffff0000, v52
	s_waitcnt vmcnt(10)
	v_and_b32_e32 v125, 0xffff0000, v50
	v_lshlrev_b32_e32 v120, 16, v52
	v_lshlrev_b32_e32 v124, 16, v50
	v_lshlrev_b32_e32 v122, 16, v53
	v_lshlrev_b32_e32 v126, 16, v51
	v_mul_f32_e32 v86, v121, v121
	v_mul_f32_e32 v87, v125, v125
	v_and_b32_e32 v123, 0xffff0000, v53
	v_and_b32_e32 v127, 0xffff0000, v51
	v_fma_f32 v84, v120, v120, v86
	v_fma_f32 v85, v124, v124, v87
	v_fma_f32 v84, v122, v122, v84
	v_fma_f32 v85, v126, v126, v85
	s_waitcnt vmcnt(9)
	v_and_b32_e32 v129, 0xffff0000, v56
	s_waitcnt vmcnt(8)
	v_and_b32_e32 v133, 0xffff0000, v54
	v_fma_f32 v84, v123, v123, v84
	v_fma_f32 v85, v127, v127, v85
	v_lshlrev_b32_e32 v128, 16, v56
	v_lshlrev_b32_e32 v132, 16, v54
	v_lshlrev_b32_e32 v130, 16, v57
	v_lshlrev_b32_e32 v134, 16, v55
	v_mul_f32_e32 v88, v133, v133
	v_mul_f32_e32 v89, v129, v129
	v_and_b32_e32 v131, 0xffff0000, v57
	v_and_b32_e32 v135, 0xffff0000, v55
	v_fma_f32 v86, v132, v132, v88
	v_fma_f32 v87, v128, v128, v89
	v_fma_f32 v86, v134, v134, v86
	v_fma_f32 v87, v130, v130, v87
	v_add_f32_e32 v84, v84, v85
	v_fma_f32 v86, v135, v135, v86
	v_fma_f32 v87, v131, v131, v87
	v_add_f32_e32 v84, v87, v84
	v_add_f32_e32 v84, v86, v84
	ds_bpermute_b32 v85, v249, v84
	s_add_i32 s2, s50, 0xffff8000
	s_waitcnt lgkmcnt(0)
	v_add_f32_e32 v84, v84, v85
	ds_bpermute_b32 v85, v248, v84
	s_mov_b32 s60, s83
	s_cmpk_gt_i32 s50, 0x7fff
	s_waitcnt lgkmcnt(0)
	v_add_f32_e32 v84, v84, v85
	ds_bpermute_b32 v85, v247, v84
	s_mov_b32 s61, s84
	s_mov_b32 s18, s85
	s_waitcnt lgkmcnt(0)
	v_add_f32_e32 v84, v84, v85
	ds_bpermute_b32 v85, v246, v84
	s_cselect_b32 s3, 0, s51
	s_cselect_b32 s2, s2, s50
	s_waitcnt lgkmcnt(0)
	v_add_f32_e32 v84, v84, v85
	ds_bpermute_b32 v85, v245, v84
	s_cselect_b32 s19, s18, s61
	s_mov_b32 s18, s86
	s_waitcnt lgkmcnt(0)
	v_add_f32_e32 v104, v84, v85
	ds_bpermute_b32 v105, v244, v104
	s_cselect_b32 s18, s18, s60
	s_lshl_b64 s[2:3], s[2:3], 12
	s_add_u32 s18, s18, s2
	s_addc_u32 s19, s19, s3
	s_and_b32 s2, s1, 0xfffff000
	s_waitcnt lgkmcnt(0)
	v_add_f32_e32 v104, v104, v105
	v_add_u32_e32 v103, s2, v100
	v_fmamk_f32 v104, v104, 0x3a800000, v218
	s_mov_b32 s2, 0x800000
	v_mul_f32_e32 v105, 0x4b800000, v104
	v_cmp_gt_f32_e32 vcc, s2, v104
	ds_read_b128 v[84:87], v100 offset:32768
	ds_read_b128 v[88:91], v100 offset:33792
	ds_read_b128 v[92:95], v103 offset:40960
	ds_read_b128 v[96:99], v103 offset:41984
	v_cndmask_b32_e32 v104, v104, v105, vcc
	v_rsq_f32_e32 v136, v104
	ds_read_b128 v[104:107], v100 offset:34816
	ds_read_b128 v[108:111], v100 offset:35840
	ds_read_b128 v[112:115], v103 offset:43008
	ds_read_b128 v[116:119], v103 offset:44032
	s_mov_b32 s62, s87
	s_mov_b32 s63, s88
	v_mul_f32_e32 v103, 0x45800000, v136
	v_cndmask_b32_e32 v136, v136, v103, vcc
	v_pk_mul_f32 v[120:121], v[136:137], v[120:121] op_sel_hi:[0,1]
	s_waitcnt lgkmcnt(7)
	v_pk_mul_f32 v[84:85], v[84:85], v[120:121]
	s_waitcnt lgkmcnt(5)
	v_pk_fma_f32 v[0:1], v[92:93], v[84:85], v[0:1]
	v_pk_mul_f32 v[84:85], v[136:137], v[122:123] op_sel_hi:[0,1]
	v_pk_mul_f32 v[84:85], v[86:87], v[84:85]
	s_nop 0
	v_pk_fma_f32 v[2:3], v[94:95], v[84:85], v[2:3]
	v_pk_mul_f32 v[84:85], v[136:137], v[124:125] op_sel_hi:[0,1]
	v_pk_mul_f32 v[84:85], v[88:89], v[84:85]
	global_store_dwordx4 v8, v[0:3], s[18:19] nt
	s_waitcnt lgkmcnt(4)
	v_pk_fma_f32 v[4:5], v[96:97], v[84:85], v[4:5]
	v_pk_mul_f32 v[84:85], v[136:137], v[126:127] op_sel_hi:[0,1]
	v_pk_mul_f32 v[84:85], v[90:91], v[84:85]
	s_nop 0
	v_pk_fma_f32 v[6:7], v[98:99], v[84:85], v[6:7]
	v_pk_mul_f32 v[84:85], v[136:137], v[128:129] op_sel_hi:[0,1]
	s_waitcnt lgkmcnt(3)
	v_pk_mul_f32 v[84:85], v[104:105], v[84:85]
	global_store_dwordx4 v8, v[4:7], s[18:19] offset:1024 nt
	s_waitcnt lgkmcnt(1)
	v_pk_fma_f32 v[10:11], v[112:113], v[84:85], v[10:11]
	v_pk_mul_f32 v[84:85], v[136:137], v[130:131] op_sel_hi:[0,1]
	v_pk_mul_f32 v[84:85], v[106:107], v[84:85]
	s_nop 0
	v_pk_fma_f32 v[12:13], v[114:115], v[84:85], v[12:13]
	v_pk_mul_f32 v[84:85], v[136:137], v[132:133] op_sel_hi:[0,1]
	v_pk_mul_f32 v[84:85], v[84:85], v[108:109]
	global_store_dwordx4 v8, v[10:13], s[18:19] offset:2048 nt
	s_waitcnt lgkmcnt(0)
	v_pk_fma_f32 v[14:15], v[116:117], v[84:85], v[14:15]
	v_pk_mul_f32 v[84:85], v[136:137], v[134:135] op_sel_hi:[0,1]
	v_pk_mul_f32 v[84:85], v[84:85], v[110:111]
	s_nop 0
	v_pk_fma_f32 v[16:17], v[118:119], v[84:85], v[16:17]
	global_store_dwordx4 v8, v[14:17], s[18:19] offset:3072 nt
.LBB0_464:
	s_mov_b32 s2, s89
	s_mov_b32 s3, s90
	s_andn2_b64 vcc, exec, s[2:3]
	s_nop 0
	v_cndmask_b32_e64 v84, 0, 1, s[2:3]
	v_cmp_ne_u32_e64 s[48:49], 1, v84
	s_cbranch_vccnz .LBB0_468
	s_waitcnt vmcnt(10)
	v_mul_f32_e32 v86, v5, v5
	v_mul_f32_e32 v87, v1, v1
	s_waitcnt vmcnt(8)
	v_fma_f32 v84, v4, v4, v86
	v_fma_f32 v85, v0, v0, v87
	v_fma_f32 v84, v6, v6, v84
	v_fma_f32 v85, v2, v2, v85
	v_fma_f32 v84, v7, v7, v84
	v_fma_f32 v85, v3, v3, v85
	v_mul_f32_e32 v88, v15, v15
	v_mul_f32_e32 v89, v11, v11
	v_add_f32_e32 v84, v84, v85
	v_fma_f32 v86, v14, v14, v88
	v_fma_f32 v87, v10, v10, v89
	v_fma_f32 v86, v16, v16, v86
	v_fma_f32 v87, v12, v12, v87
	v_fma_f32 v86, v17, v17, v86
	v_fma_f32 v87, v13, v13, v87
	v_add_f32_e32 v84, v87, v84
	v_add_f32_e32 v84, v86, v84
	s_mov_b32 s2, 0x800000
	s_and_b32 s1, s1, 0xfffff000
	ds_bpermute_b32 v86, v249, v84
	v_add_u32_e32 v98, s1, v101
	ds_read_b128 v[104:107], v98
	s_mov_b32 s60, s83
	s_mov_b32 s62, s87
	s_waitcnt lgkmcnt(1)
	v_add_f32_e32 v84, v84, v86
	s_mov_b32 s63, s88
	s_mov_b32 s61, s84
	ds_bpermute_b32 v86, v248, v84
	s_waitcnt lgkmcnt(0)
	v_add_f32_e32 v84, v84, v86
	s_nop 1
	ds_bpermute_b32 v86, v247, v84
	s_waitcnt lgkmcnt(0)
	v_add_f32_e32 v84, v84, v86
	s_nop 1
	ds_bpermute_b32 v86, v246, v84
	s_waitcnt lgkmcnt(0)
	v_add_f32_e32 v84, v84, v86
	s_nop 1
	ds_bpermute_b32 v86, v245, v84
	s_waitcnt lgkmcnt(0)
	v_add_f32_e32 v84, v84, v86
	s_nop 1
	ds_bpermute_b32 v85, v244, v84
	ds_read_b128 v[86:89], v100 offset:36864
	s_waitcnt lgkmcnt(1)
	v_add_f32_e32 v84, v84, v85
	v_fmamk_f32 v84, v84, 0x3a800000, v218
	v_cmp_gt_f32_e32 vcc, s2, v84
	v_mul_f32_e32 v85, 0x4b800000, v84
	s_nop 0
	v_cndmask_b32_e32 v84, v84, v85, vcc
	v_rsq_f32_e32 v84, v84
	s_nop 0
	v_mul_f32_e32 v85, 0x45800000, v84
	v_cndmask_b32_e32 v84, v84, v85, vcc
	v_add_u32_e32 v85, s1, v102
	ds_read_b128 v[108:111], v85
	v_pk_mul_f32 v[90:91], v[0:1], v[84:85] op_sel_hi:[1,0]
	s_mov_b32 s1, 0xb00000
	s_waitcnt lgkmcnt(1)
	v_pk_mul_f32 v[86:87], v[86:87], v[90:91]
	v_pk_add_f32 v[90:91], v[104:105], 1.0 op_sel_hi:[1,0]
	v_pk_mul_f32 v[118:119], v[4:5], v[84:85] op_sel_hi:[1,0]
	s_waitcnt lgkmcnt(0)
	v_pk_fma_f32 v[112:113], v[90:91], v[86:87], v[108:109]
	v_pk_mul_f32 v[86:87], v[2:3], v[84:85] op_sel_hi:[1,0]
	s_nop 0
	v_pk_mul_f32 v[86:87], v[88:89], v[86:87]
	v_pk_add_f32 v[88:89], v[106:107], 1.0 op_sel_hi:[1,0]
	s_nop 0
	v_pk_fma_f32 v[110:111], v[88:89], v[86:87], v[110:111]
	v_lshl_add_u64 v[86:87], s[62:63], 0, v[70:71]
	v_add_co_u32_e32 v86, vcc, s1, v86
	v_cvt_pk_bf16_f32 v88, v112, v113
	v_cvt_pk_bf16_f32 v89, v110, v111
	v_addc_co_u32_e32 v87, vcc, 0, v87, vcc
	global_store_dwordx2 v[86:87], v[88:89], off
	ds_read_b128 v[88:91], v100
	s_waitcnt lgkmcnt(0)
	v_mul_f32_e32 v89, v89, v113
	v_fmac_f32_e32 v89, v88, v112
	v_fmac_f32_e32 v89, v90, v110
	v_fmac_f32_e32 v89, v91, v111
	v_add_f32_e32 v107, 0, v89
	ds_read_b128 v[88:91], v100 offset:4096
	s_waitcnt lgkmcnt(0)
	v_mul_f32_e32 v89, v89, v113
	v_fmac_f32_e32 v89, v88, v112
	v_fmac_f32_e32 v89, v90, v110
	v_fmac_f32_e32 v89, v91, v111
	v_add_f32_e32 v109, 0, v89
	ds_read_b128 v[88:91], v100 offset:8192
	s_waitcnt lgkmcnt(0)
	v_mul_f32_e32 v89, v89, v113
	v_fmac_f32_e32 v89, v88, v112
	v_fmac_f32_e32 v89, v90, v110
	v_fmac_f32_e32 v89, v91, v111
	v_add_f32_e32 v108, 0, v89
	ds_read_b128 v[88:91], v100 offset:12288
	s_waitcnt lgkmcnt(0)
	v_mul_f32_e32 v89, v89, v113
	v_fmac_f32_e32 v89, v88, v112
	v_fmac_f32_e32 v89, v90, v110
	v_fmac_f32_e32 v89, v91, v111
	v_add_f32_e32 v106, 0, v89
	ds_read_b128 v[88:91], v100 offset:16384
	s_waitcnt lgkmcnt(0)
	v_mul_f32_e32 v89, v89, v113
	v_fmac_f32_e32 v89, v88, v112
	v_fmac_f32_e32 v89, v90, v110
	v_fmac_f32_e32 v89, v91, v111
	v_add_f32_e32 v105, 0, v89
	ds_read_b128 v[88:91], v100 offset:20480
	s_waitcnt lgkmcnt(0)
	v_mul_f32_e32 v89, v89, v113
	v_fmac_f32_e32 v89, v88, v112
	v_fmac_f32_e32 v89, v90, v110
	v_fmac_f32_e32 v89, v91, v111
	v_add_f32_e32 v104, 0, v89
	ds_read_b128 v[88:91], v100 offset:24576
	s_waitcnt lgkmcnt(0)
	v_mul_f32_e32 v89, v89, v113
	v_fmac_f32_e32 v89, v88, v112
	v_fmac_f32_e32 v89, v90, v110
	v_fmac_f32_e32 v89, v91, v111
	v_add_f32_e32 v103, 0, v89
	ds_read_b128 v[88:91], v100 offset:28672
	s_waitcnt lgkmcnt(0)
	v_mul_f32_e32 v89, v113, v89
	v_fmac_f32_e32 v89, v112, v88
	v_fmac_f32_e32 v89, v110, v90
	v_fmac_f32_e32 v89, v111, v91
	v_add_f32_e32 v99, 0, v89
	ds_read_b128 v[88:91], v100 offset:37888
	ds_read_b128 v[110:113], v98 offset:1024
	ds_read_b128 v[114:117], v85 offset:1024
	s_waitcnt lgkmcnt(2)
	v_pk_mul_f32 v[88:89], v[118:119], v[88:89]
	s_waitcnt lgkmcnt(1)
	v_pk_add_f32 v[110:111], v[110:111], 1.0 op_sel_hi:[1,0]
	s_waitcnt lgkmcnt(0)
	v_pk_fma_f32 v[88:89], v[88:89], v[110:111], v[114:115]
	v_pk_mul_f32 v[110:111], v[6:7], v[84:85] op_sel_hi:[1,0]
	s_nop 0
	v_pk_mul_f32 v[90:91], v[110:111], v[90:91]
	v_pk_add_f32 v[110:111], v[112:113], 1.0 op_sel_hi:[1,0]
	s_nop 0
	v_pk_fma_f32 v[90:91], v[90:91], v[110:111], v[116:117]
	v_cvt_pk_bf16_f32 v110, v88, v89
	v_cvt_pk_bf16_f32 v111, v90, v91
	global_store_dwordx2 v[86:87], v[110:111], off offset:512
	ds_read_b128 v[110:113], v100 offset:1024
	s_waitcnt lgkmcnt(0)
	v_mul_f32_e32 v111, v89, v111
	v_fmac_f32_e32 v111, v88, v110
	v_fmac_f32_e32 v111, v90, v112
	v_fmac_f32_e32 v111, v91, v113
	v_add_f32_e32 v107, v107, v111
	ds_read_b128 v[110:113], v100 offset:5120
	s_waitcnt lgkmcnt(0)
	v_mul_f32_e32 v111, v89, v111
	v_fmac_f32_e32 v111, v88, v110
	v_fmac_f32_e32 v111, v90, v112
	v_fmac_f32_e32 v111, v91, v113
	v_add_f32_e32 v116, v109, v111
	ds_read_b128 v[110:113], v100 offset:9216
	s_waitcnt lgkmcnt(0)
	v_mul_f32_e32 v109, v89, v111
	v_fmac_f32_e32 v109, v88, v110
	v_fmac_f32_e32 v109, v90, v112
	v_fmac_f32_e32 v109, v91, v113
	v_add_f32_e32 v117, v108, v109
	ds_read_b128 v[108:111], v100 offset:13312
	s_waitcnt lgkmcnt(0)
	v_mul_f32_e32 v109, v89, v109
	v_fmac_f32_e32 v109, v88, v108
	v_fmac_f32_e32 v109, v90, v110
	v_fmac_f32_e32 v109, v91, v111
	v_add_f32_e32 v106, v106, v109
	ds_read_b128 v[108:111], v100 offset:17408
	s_waitcnt lgkmcnt(0)
	v_mul_f32_e32 v109, v89, v109
	v_fmac_f32_e32 v109, v88, v108
	v_fmac_f32_e32 v109, v90, v110
	v_fmac_f32_e32 v109, v91, v111
	v_add_f32_e32 v118, v105, v109
	ds_read_b128 v[108:111], v100 offset:21504
	s_waitcnt lgkmcnt(0)
	v_mul_f32_e32 v105, v89, v109
	v_fmac_f32_e32 v105, v88, v108
	v_fmac_f32_e32 v105, v90, v110
	v_fmac_f32_e32 v105, v91, v111
	ds_read_b128 v[108:111], v100 offset:25600
	v_add_f32_e32 v119, v104, v105
	s_waitcnt lgkmcnt(0)
	v_mul_f32_e32 v104, v89, v109
	v_fmac_f32_e32 v104, v88, v108
	v_fmac_f32_e32 v104, v90, v110
	v_fmac_f32_e32 v104, v91, v111
	ds_read_b128 v[108:111], v100 offset:29696
	v_add_f32_e32 v120, v103, v104
	v_pk_mul_f32 v[104:105], v[10:11], v[84:85] op_sel_hi:[1,0]
	s_waitcnt lgkmcnt(0)
	v_mul_f32_e32 v89, v89, v109
	v_fmac_f32_e32 v89, v88, v108
	v_fmac_f32_e32 v89, v90, v110
	v_fmac_f32_e32 v89, v91, v111
	v_add_f32_e32 v121, v99, v89
	ds_read_b128 v[88:91], v100 offset:38912
	ds_read_b128 v[108:111], v98 offset:2048
	ds_read_b128 v[112:115], v85 offset:2048
	s_waitcnt lgkmcnt(2)
	v_pk_mul_f32 v[88:89], v[104:105], v[88:89]
	s_waitcnt lgkmcnt(1)
	v_pk_add_f32 v[104:105], v[108:109], 1.0 op_sel_hi:[1,0]
	s_waitcnt lgkmcnt(0)
	v_pk_fma_f32 v[112:113], v[88:89], v[104:105], v[112:113]
	v_pk_mul_f32 v[88:89], v[12:13], v[84:85] op_sel_hi:[1,0]
	s_nop 0
	v_pk_mul_f32 v[88:89], v[88:89], v[90:91]
	v_pk_add_f32 v[90:91], v[110:111], 1.0 op_sel_hi:[1,0]
	s_nop 0
	v_pk_fma_f32 v[110:111], v[88:89], v[90:91], v[114:115]
	v_cvt_pk_bf16_f32 v88, v112, v113
	v_cvt_pk_bf16_f32 v89, v110, v111
	global_store_dwordx2 v[86:87], v[88:89], off offset:1024
	ds_read_b128 v[88:91], v100 offset:2048
	s_waitcnt lgkmcnt(0)
	v_mul_f32_e32 v89, v113, v89
	v_fmac_f32_e32 v89, v112, v88
	v_fmac_f32_e32 v89, v110, v90
	v_fmac_f32_e32 v89, v111, v91
	v_add_f32_e32 v105, v107, v89
	ds_read_b128 v[88:91], v100 offset:6144
	s_waitcnt lgkmcnt(0)
	v_mul_f32_e32 v89, v113, v89
	v_fmac_f32_e32 v89, v112, v88
	v_fmac_f32_e32 v89, v110, v90
	v_fmac_f32_e32 v89, v111, v91
	v_add_f32_e32 v122, v116, v89
	ds_read_b128 v[88:91], v100 offset:10240
	s_waitcnt lgkmcnt(0)
	v_mul_f32_e32 v89, v113, v89
	v_fmac_f32_e32 v89, v112, v88
	v_fmac_f32_e32 v89, v110, v90
	v_fmac_f32_e32 v89, v111, v91
	v_add_f32_e32 v123, v117, v89
	ds_read_b128 v[88:91], v100 offset:14336
	s_waitcnt lgkmcnt(0)
	v_mul_f32_e32 v89, v113, v89
	v_fmac_f32_e32 v89, v112, v88
	v_fmac_f32_e32 v89, v110, v90
	v_fmac_f32_e32 v89, v111, v91
	v_add_f32_e32 v104, v106, v89
	ds_read_b128 v[88:91], v100 offset:18432
	ds_read_b128 v[106:109], v100 offset:30720
	s_waitcnt lgkmcnt(1)
	v_mul_f32_e32 v89, v113, v89
	v_fmac_f32_e32 v89, v112, v88
	v_fmac_f32_e32 v89, v110, v90
	v_fmac_f32_e32 v89, v111, v91
	v_add_f32_e32 v103, v118, v89
	ds_read_b128 v[88:91], v100 offset:22528
	s_waitcnt lgkmcnt(0)
	v_mul_f32_e32 v89, v113, v89
	v_fmac_f32_e32 v89, v112, v88
	v_fmac_f32_e32 v89, v110, v90
	v_fmac_f32_e32 v89, v111, v91
	v_add_f32_e32 v99, v119, v89
	ds_read_b128 v[88:91], v100 offset:26624
	s_waitcnt lgkmcnt(0)
	v_mul_f32_e32 v89, v113, v89
	v_fmac_f32_e32 v89, v112, v88
	v_mul_f32_e32 v88, v113, v107
	v_fmac_f32_e32 v88, v112, v106
	v_fmac_f32_e32 v89, v110, v90
	v_fmac_f32_e32 v88, v110, v108
	v_fmac_f32_e32 v89, v111, v91
	v_fmac_f32_e32 v88, v111, v109
	ds_read_b128 v[106:109], v100 offset:39936
	ds_read_b128 v[110:113], v98 offset:3072
	ds_read_b128 v[114:117], v85 offset:3072
	v_add_f32_e32 v91, v120, v89
	v_add_f32_e32 v90, v121, v88
	v_pk_mul_f32 v[88:89], v[14:15], v[84:85] op_sel_hi:[1,0]
	v_pk_mul_f32 v[84:85], v[16:17], v[84:85] op_sel_hi:[1,0]
	s_waitcnt lgkmcnt(2)
	v_pk_mul_f32 v[88:89], v[88:89], v[106:107]
	s_waitcnt lgkmcnt(1)
	v_pk_add_f32 v[106:107], v[110:111], 1.0 op_sel_hi:[1,0]
	v_pk_mul_f32 v[84:85], v[84:85], v[108:109]
	s_waitcnt lgkmcnt(0)
	v_pk_fma_f32 v[88:89], v[88:89], v[106:107], v[114:115]
	v_pk_add_f32 v[106:107], v[112:113], 1.0 op_sel_hi:[1,0]
	s_nop 0
	v_pk_fma_f32 v[84:85], v[84:85], v[106:107], v[116:117]
	v_cvt_pk_bf16_f32 v106, v88, v89
	v_cvt_pk_bf16_f32 v107, v84, v85
	global_store_dwordx2 v[86:87], v[106:107], off offset:1536
	ds_read_b128 v[106:109], v100 offset:3072
	s_waitcnt lgkmcnt(0)
	v_mul_f32_e32 v86, v89, v107
	v_fmac_f32_e32 v86, v88, v106
	v_fmac_f32_e32 v86, v84, v108
	v_fmac_f32_e32 v86, v85, v109
	ds_read_b128 v[106:109], v100 offset:7168
	v_add_f32_e32 v86, v105, v86
	s_waitcnt lgkmcnt(0)
	v_mul_f32_e32 v87, v89, v107
	v_fmac_f32_e32 v87, v88, v106
	v_fmac_f32_e32 v87, v84, v108
	v_fmac_f32_e32 v87, v85, v109
	ds_read_b128 v[106:109], v100 offset:11264
	v_add_f32_e32 v87, v122, v87
	s_waitcnt lgkmcnt(0)
	v_mul_f32_e32 v98, v89, v107
	v_fmac_f32_e32 v98, v88, v106
	v_fmac_f32_e32 v98, v84, v108
	v_fmac_f32_e32 v98, v85, v109
	ds_read_b128 v[106:109], v100 offset:15360
	v_add_f32_e32 v98, v123, v98
	s_waitcnt lgkmcnt(0)
	v_mul_f32_e32 v105, v89, v107
	v_fmac_f32_e32 v105, v88, v106
	v_fmac_f32_e32 v105, v84, v108
	v_fmac_f32_e32 v105, v85, v109
	v_add_f32_e32 v108, v104, v105
	ds_read_b128 v[104:107], v100 offset:19456
	s_waitcnt lgkmcnt(0)
	v_mul_f32_e32 v105, v89, v105
	v_fmac_f32_e32 v105, v88, v104
	v_fmac_f32_e32 v105, v84, v106
	v_fmac_f32_e32 v105, v85, v107
	v_add_f32_e32 v103, v103, v105
	ds_read_b128 v[104:107], v100 offset:23552
	s_waitcnt lgkmcnt(0)
	v_mul_f32_e32 v105, v89, v105
	v_fmac_f32_e32 v105, v88, v104
	v_fmac_f32_e32 v105, v84, v106
	v_fmac_f32_e32 v105, v85, v107
	v_add_f32_e32 v99, v99, v105
	ds_read_b128 v[104:107], v100 offset:27648
	s_waitcnt lgkmcnt(0)
	v_mul_f32_e32 v105, v89, v105
	v_fmac_f32_e32 v105, v88, v104
	v_fmac_f32_e32 v105, v84, v106
	v_fmac_f32_e32 v105, v85, v107
	v_add_f32_e32 v91, v91, v105
	ds_read_b128 v[104:107], v100 offset:31744
	s_waitcnt lgkmcnt(0)
	v_mul_f32_e32 v89, v89, v105
	v_fmac_f32_e32 v89, v88, v104
	v_fmac_f32_e32 v89, v84, v106
	v_fmac_f32_e32 v89, v85, v107
	v_cndmask_b32_e64 v85, v103, v86, s[40:41]
	v_cndmask_b32_e64 v86, v86, v103, s[40:41]
	ds_bpermute_b32 v86, v249, v86
	v_cndmask_b32_e64 v88, v98, v91, s[40:41]
	ds_bpermute_b32 v88, v249, v88
	v_add_f32_e32 v84, v90, v89
	s_waitcnt lgkmcnt(1)
	v_add_f32_e32 v85, v85, v86
	v_cndmask_b32_e64 v86, v99, v87, s[40:41]
	v_cndmask_b32_e64 v87, v87, v99, s[40:41]
	ds_bpermute_b32 v87, v249, v87
	s_waitcnt lgkmcnt(0)
	v_add_f32_e32 v86, v86, v87
	v_cndmask_b32_e64 v87, v91, v98, s[40:41]
	v_add_f32_e32 v87, v87, v88
	v_cndmask_b32_e64 v88, v84, v108, s[40:41]
	v_cndmask_b32_e64 v84, v108, v84, s[40:41]
	ds_bpermute_b32 v84, v249, v84
	s_waitcnt lgkmcnt(0)
	v_add_f32_e32 v84, v88, v84
	v_cndmask_b32_e64 v88, v87, v85, s[42:43]
	v_cndmask_b32_e64 v85, v85, v87, s[42:43]
	v_cndmask_b32_e64 v87, v84, v86, s[42:43]
	v_cndmask_b32_e64 v84, v86, v84, s[42:43]
	ds_bpermute_b32 v85, v248, v85
	ds_bpermute_b32 v84, v248, v84
	s_waitcnt lgkmcnt(1)
	v_add_f32_e32 v85, v88, v85
	s_waitcnt lgkmcnt(0)
	v_add_f32_e32 v84, v87, v84
	v_cndmask_b32_e64 v86, v84, v85, s[44:45]
	v_cndmask_b32_e64 v84, v85, v84, s[44:45]
	ds_bpermute_b32 v84, v247, v84
	s_waitcnt lgkmcnt(0)
	v_add_f32_e32 v84, v86, v84
	ds_bpermute_b32 v85, v246, v84
	s_waitcnt lgkmcnt(0)
	v_add_f32_e32 v84, v84, v85
	ds_bpermute_b32 v85, v245, v84
	s_waitcnt lgkmcnt(0)
	v_add_f32_e32 v84, v84, v85
	ds_bpermute_b32 v85, v244, v84
	s_and_saveexec_b64 s[18:19], s[46:47]
	s_cbranch_execz .LBB0_467
	s_mov_b32 s60, s83
	s_mov_b32 s62, s87
	s_mov_b32 s63, s88
	s_waitcnt lgkmcnt(0)
	v_add_f32_e32 v86, v84, v85
	s_mov_b32 s61, s84
	v_lshl_add_u64 v[84:85], s[62:63], 0, v[68:69]
	global_store_dword v[84:85], v86, off

.LBB0_468:
	s_add_u32 s56, s37, s50
	s_cmp_ge_i32 s56, s26
	s_cbranch_scc1 .LBB0_481
	s_add_i32 s1, s4, s50
	s_cmp_lt_i32 s1, s26
	s_cselect_b32 s24, s1, s0
	s_cmpk_gt_i32 s24, 0x7fff
	s_mov_b64 s[28:29], -1
	s_cbranch_scc0 .LBB0_471
	s_add_i32 s26, s24, 0xffff8000
	s_lshl_b64 s[2:3], s[26:27], 12
	s_mov_b32 s1, s78
	s_add_u32 s18, s1, s2
	s_mov_b32 s1, s79
	s_mov_b32 s26, s80
	s_addc_u32 s19, s1, s3
	s_mov_b32 s25, s27
	s_mov_b64 s[28:29], 0

.LBB0_486:
	s_waitcnt vmcnt(11)
	v_and_b32_e32 v121, 0xffff0000, v60
	s_waitcnt vmcnt(10)
	v_and_b32_e32 v125, 0xffff0000, v58
	v_lshlrev_b32_e32 v120, 16, v60
	v_lshlrev_b32_e32 v124, 16, v58
	v_lshlrev_b32_e32 v122, 16, v61
	v_lshlrev_b32_e32 v126, 16, v59
	v_mul_f32_e32 v86, v121, v121
	v_mul_f32_e32 v87, v125, v125
	v_and_b32_e32 v123, 0xffff0000, v61
	v_and_b32_e32 v127, 0xffff0000, v59
	v_fma_f32 v84, v120, v120, v86
	v_fma_f32 v85, v124, v124, v87
	v_fma_f32 v84, v122, v122, v84
	v_fma_f32 v85, v126, v126, v85
	s_waitcnt vmcnt(9)
	v_and_b32_e32 v129, 0xffff0000, v74
	s_waitcnt vmcnt(8)
	v_and_b32_e32 v133, 0xffff0000, v72
	v_fma_f32 v84, v123, v123, v84
	v_fma_f32 v85, v127, v127, v85
	v_lshlrev_b32_e32 v128, 16, v74
	v_lshlrev_b32_e32 v132, 16, v72
	v_lshlrev_b32_e32 v130, 16, v75
	v_lshlrev_b32_e32 v134, 16, v73
	v_mul_f32_e32 v88, v133, v133
	v_mul_f32_e32 v89, v129, v129
	v_and_b32_e32 v131, 0xffff0000, v75
	v_and_b32_e32 v135, 0xffff0000, v73
	v_fma_f32 v86, v132, v132, v88
	v_fma_f32 v87, v128, v128, v89
	v_fma_f32 v86, v134, v134, v86
	v_fma_f32 v87, v130, v130, v87
	v_add_f32_e32 v84, v84, v85
	v_fma_f32 v86, v135, v135, v86
	v_fma_f32 v87, v131, v131, v87
	v_add_f32_e32 v84, v87, v84
	v_add_f32_e32 v84, v86, v84
	ds_bpermute_b32 v85, v249, v84
	s_add_i32 s2, s56, 0xffff8000
	s_waitcnt lgkmcnt(0)
	v_add_f32_e32 v84, v84, v85
	ds_bpermute_b32 v85, v248, v84
	s_ashr_i32 s3, s56, 31
	s_mov_b32 s60, s83
	s_waitcnt lgkmcnt(0)
	v_add_f32_e32 v84, v84, v85
	ds_bpermute_b32 v85, v247, v84
	s_cmpk_gt_i32 s56, 0x7fff
	s_mov_b32 s61, s84
	s_waitcnt lgkmcnt(0)
	v_add_f32_e32 v84, v84, v85
	ds_bpermute_b32 v85, v246, v84
	s_mov_b32 s18, s85
	s_cselect_b32 s3, 0, s3
	s_waitcnt lgkmcnt(0)
	v_add_f32_e32 v84, v84, v85
	ds_bpermute_b32 v85, v245, v84
	s_cselect_b32 s2, s2, s56
	s_cselect_b32 s19, s18, s61
	s_waitcnt lgkmcnt(0)
	v_add_f32_e32 v104, v84, v85
	ds_bpermute_b32 v105, v244, v104
	s_mov_b32 s18, s86
	s_cselect_b32 s18, s18, s60
	s_lshl_b64 s[2:3], s[2:3], 12
	s_add_u32 s18, s18, s2
	s_addc_u32 s19, s19, s3
	s_and_b32 s2, s1, 0xfffff000
	s_waitcnt lgkmcnt(0)
	v_add_f32_e32 v104, v104, v105
	v_add_u32_e32 v103, s2, v100
	v_fmamk_f32 v104, v104, 0x3a800000, v218
	s_mov_b32 s2, 0x800000
	v_mul_f32_e32 v105, 0x4b800000, v104
	v_cmp_gt_f32_e32 vcc, s2, v104
	ds_read_b128 v[84:87], v100 offset:32768
	ds_read_b128 v[88:91], v100 offset:33792
	ds_read_b128 v[92:95], v103 offset:40960
	ds_read_b128 v[96:99], v103 offset:41984
	v_cndmask_b32_e32 v104, v104, v105, vcc
	v_rsq_f32_e32 v136, v104
	ds_read_b128 v[104:107], v100 offset:34816
	ds_read_b128 v[108:111], v100 offset:35840
	ds_read_b128 v[112:115], v103 offset:43008
	ds_read_b128 v[116:119], v103 offset:44032
	s_mov_b32 s62, s87
	s_mov_b32 s63, s88
	v_mul_f32_e32 v103, 0x45800000, v136
	v_cndmask_b32_e32 v136, v136, v103, vcc
	v_pk_mul_f32 v[120:121], v[136:137], v[120:121] op_sel_hi:[0,1]
	s_waitcnt lgkmcnt(7)
	v_pk_mul_f32 v[84:85], v[84:85], v[120:121]
	s_waitcnt lgkmcnt(5)
	v_pk_fma_f32 v[18:19], v[92:93], v[84:85], v[18:19]
	v_pk_mul_f32 v[84:85], v[136:137], v[122:123] op_sel_hi:[0,1]
	v_pk_mul_f32 v[84:85], v[86:87], v[84:85]
	s_nop 0
	v_pk_fma_f32 v[20:21], v[94:95], v[84:85], v[20:21]
	v_pk_mul_f32 v[84:85], v[136:137], v[124:125] op_sel_hi:[0,1]
	v_pk_mul_f32 v[84:85], v[88:89], v[84:85]
	global_store_dwordx4 v8, v[18:21], s[18:19] nt
	s_waitcnt lgkmcnt(4)
	v_pk_fma_f32 v[22:23], v[96:97], v[84:85], v[22:23]
	v_pk_mul_f32 v[84:85], v[136:137], v[126:127] op_sel_hi:[0,1]
	v_pk_mul_f32 v[84:85], v[90:91], v[84:85]
	s_nop 0
	v_pk_fma_f32 v[24:25], v[98:99], v[84:85], v[24:25]
	v_pk_mul_f32 v[84:85], v[136:137], v[128:129] op_sel_hi:[0,1]
	s_waitcnt lgkmcnt(3)
	v_pk_mul_f32 v[84:85], v[104:105], v[84:85]
	global_store_dwordx4 v8, v[22:25], s[18:19] offset:1024 nt
	s_waitcnt lgkmcnt(1)
	v_pk_fma_f32 v[26:27], v[112:113], v[84:85], v[26:27]
	v_pk_mul_f32 v[84:85], v[136:137], v[130:131] op_sel_hi:[0,1]
	v_pk_mul_f32 v[84:85], v[106:107], v[84:85]
	s_nop 0
	v_pk_fma_f32 v[28:29], v[114:115], v[84:85], v[28:29]
	v_pk_mul_f32 v[84:85], v[136:137], v[132:133] op_sel_hi:[0,1]
	v_pk_mul_f32 v[84:85], v[84:85], v[108:109]
	global_store_dwordx4 v8, v[26:29], s[18:19] offset:2048 nt
	s_waitcnt lgkmcnt(0)
	v_pk_fma_f32 v[30:31], v[116:117], v[84:85], v[30:31]
	v_pk_mul_f32 v[84:85], v[136:137], v[134:135] op_sel_hi:[0,1]
	v_pk_mul_f32 v[84:85], v[84:85], v[110:111]
	s_nop 0
	v_pk_fma_f32 v[32:33], v[118:119], v[84:85], v[32:33]
	global_store_dwordx4 v8, v[30:33], s[18:19] offset:3072 nt
	s_and_b64 vcc, exec, s[48:49]
	s_cbranch_vccnz .LBB0_481
.LBB0_487:
	s_waitcnt vmcnt(10)
	v_mul_f32_e32 v86, v23, v23
	v_mul_f32_e32 v87, v19, v19
	s_waitcnt vmcnt(8)
	v_fma_f32 v84, v22, v22, v86
	v_fma_f32 v85, v18, v18, v87
	v_fma_f32 v84, v24, v24, v84
	v_fma_f32 v85, v20, v20, v85
	v_fma_f32 v84, v25, v25, v84
	v_fma_f32 v85, v21, v21, v85
	v_mul_f32_e32 v88, v31, v31
	v_mul_f32_e32 v89, v27, v27
	v_add_f32_e32 v84, v84, v85
	v_fma_f32 v86, v30, v30, v88
	v_fma_f32 v87, v26, v26, v89
	v_fma_f32 v86, v32, v32, v86
	v_fma_f32 v87, v28, v28, v87
	v_fma_f32 v86, v33, v33, v86
	v_fma_f32 v87, v29, v29, v87
	v_add_f32_e32 v84, v87, v84
	v_add_f32_e32 v84, v86, v84
	s_mov_b32 s2, 0x800000
	s_and_b32 s1, s1, 0xfffff000
	ds_bpermute_b32 v86, v249, v84
	v_add_u32_e32 v98, s1, v101
	ds_read_b128 v[94:97], v98
	v_add_u32_e32 v93, s1, v102
	ds_read_b128 v[110:113], v93
	s_waitcnt lgkmcnt(2)
	v_add_f32_e32 v84, v84, v86
	s_ashr_i32 s57, s56, 31
	ds_read_b128 v[114:117], v100
	ds_bpermute_b32 v86, v248, v84
	s_waitcnt lgkmcnt(0)
	v_add_f32_e32 v84, v84, v86
	s_nop 1
	ds_bpermute_b32 v86, v247, v84
	s_waitcnt lgkmcnt(0)
	v_add_f32_e32 v84, v84, v86
	s_nop 1
	ds_bpermute_b32 v86, v246, v84
	s_waitcnt lgkmcnt(0)
	v_add_f32_e32 v84, v84, v86
	s_nop 1
	ds_bpermute_b32 v86, v245, v84
	s_waitcnt lgkmcnt(0)
	v_add_f32_e32 v84, v84, v86
	s_nop 1
	ds_bpermute_b32 v85, v244, v84
	ds_read_b128 v[86:89], v100 offset:36864
	s_waitcnt lgkmcnt(1)
	v_add_f32_e32 v84, v84, v85
	v_fmamk_f32 v84, v84, 0x3a800000, v218
	v_cmp_gt_f32_e32 vcc, s2, v84
	v_mul_f32_e32 v85, 0x4b800000, v84
	s_lshl_b64 s[2:3], s[56:57], 11
	v_cndmask_b32_e32 v84, v84, v85, vcc
	v_rsq_f32_e32 v84, v84
	s_nop 0
	v_mul_f32_e32 v85, 0x45800000, v84
	v_cndmask_b32_e32 v92, v84, v85, vcc
	v_pk_mul_f32 v[84:85], v[18:19], v[92:93] op_sel_hi:[1,0]
	v_pk_mul_f32 v[118:119], v[22:23], v[92:93] op_sel_hi:[1,0]
	s_waitcnt lgkmcnt(0)
	v_pk_mul_f32 v[84:85], v[86:87], v[84:85]
	v_pk_add_f32 v[86:87], v[94:95], 1.0 op_sel_hi:[1,0]
	s_nop 0
	v_pk_fma_f32 v[86:87], v[86:87], v[84:85], v[110:111]
	v_pk_mul_f32 v[84:85], v[20:21], v[92:93] op_sel_hi:[1,0]
	v_mul_f32_e32 v94, v115, v87
	v_pk_mul_f32 v[84:85], v[88:89], v[84:85]
	v_pk_add_f32 v[88:89], v[96:97], 1.0 op_sel_hi:[1,0]
	v_fmac_f32_e32 v94, v114, v86
	v_pk_fma_f32 v[84:85], v[88:89], v[84:85], v[112:113]
	ds_read_b128 v[88:91], v100 offset:4096
	v_fmac_f32_e32 v94, v116, v84
	v_fmac_f32_e32 v94, v117, v85
	v_add_f32_e32 v109, 0, v94
	ds_read_b128 v[94:97], v100 offset:8192
	s_waitcnt lgkmcnt(1)
	v_mul_f32_e32 v89, v89, v87
	v_fmac_f32_e32 v89, v88, v86
	v_fmac_f32_e32 v89, v90, v84
	v_fmac_f32_e32 v89, v91, v85
	v_add_f32_e32 v122, 0, v89
	ds_read_b128 v[88:91], v100 offset:12288
	s_waitcnt lgkmcnt(1)
	v_mul_f32_e32 v95, v95, v87
	v_fmac_f32_e32 v95, v94, v86
	v_fmac_f32_e32 v95, v96, v84
	v_fmac_f32_e32 v95, v97, v85
	v_add_f32_e32 v123, 0, v95
	ds_read_b128 v[94:97], v100 offset:16384
	s_waitcnt lgkmcnt(1)
	v_mul_f32_e32 v89, v89, v87
	v_fmac_f32_e32 v89, v88, v86
	v_fmac_f32_e32 v89, v90, v84
	v_fmac_f32_e32 v89, v91, v85
	v_add_f32_e32 v99, 0, v89
	ds_read_b128 v[88:91], v100 offset:20480
	ds_read_b128 v[110:113], v100 offset:24576
	s_waitcnt lgkmcnt(2)
	v_mul_f32_e32 v95, v95, v87
	v_fmac_f32_e32 v95, v94, v86
	v_fmac_f32_e32 v95, v96, v84
	s_waitcnt lgkmcnt(1)
	v_mul_f32_e32 v89, v89, v87
	v_fmac_f32_e32 v89, v88, v86
	v_fmac_f32_e32 v89, v90, v84
	v_fmac_f32_e32 v95, v97, v85
	v_fmac_f32_e32 v89, v91, v85
	v_add_f32_e32 v96, 0, v95
	v_add_f32_e32 v95, 0, v89
	ds_read_b128 v[88:91], v100 offset:28672
	s_waitcnt lgkmcnt(1)
	v_mul_f32_e32 v94, v111, v87
	v_fmac_f32_e32 v94, v110, v86
	v_fmac_f32_e32 v94, v112, v84
	v_fmac_f32_e32 v94, v113, v85
	s_waitcnt lgkmcnt(0)
	v_mul_f32_e32 v97, v87, v89
	v_fmac_f32_e32 v97, v86, v88
	v_fmac_f32_e32 v97, v84, v90
	v_fmac_f32_e32 v97, v85, v91
	ds_read_b128 v[88:91], v100 offset:37888
	ds_read_b128 v[110:113], v98 offset:1024
	ds_read_b128 v[114:117], v93 offset:1024
	v_add_f32_e32 v94, 0, v94
	v_add_f32_e32 v97, 0, v97
	s_waitcnt lgkmcnt(2)
	v_pk_mul_f32 v[88:89], v[118:119], v[88:89]
	ds_read_b128 v[118:121], v100 offset:1024
	s_waitcnt lgkmcnt(2)
	v_pk_add_f32 v[110:111], v[110:111], 1.0 op_sel_hi:[1,0]
	v_cvt_pk_bf16_f32 v86, v86, v87
	s_waitcnt lgkmcnt(1)
	v_pk_fma_f32 v[88:89], v[88:89], v[110:111], v[114:115]
	v_pk_mul_f32 v[110:111], v[24:25], v[92:93] op_sel_hi:[1,0]
	s_nop 0
	v_pk_mul_f32 v[90:91], v[110:111], v[90:91]
	v_pk_add_f32 v[110:111], v[112:113], 1.0 op_sel_hi:[1,0]
	s_nop 0
	v_pk_fma_f32 v[90:91], v[90:91], v[110:111], v[116:117]
	ds_read_b128 v[110:113], v100 offset:5120
	s_waitcnt lgkmcnt(1)
	v_mul_f32_e32 v114, v89, v119
	v_fmac_f32_e32 v114, v88, v118
	v_fmac_f32_e32 v114, v90, v120
	v_fmac_f32_e32 v114, v91, v121
	v_add_f32_e32 v109, v109, v114
	ds_read_b128 v[114:117], v100 offset:9216
	s_waitcnt lgkmcnt(1)
	v_mul_f32_e32 v111, v89, v111
	v_fmac_f32_e32 v111, v88, v110
	v_fmac_f32_e32 v111, v90, v112
	v_fmac_f32_e32 v111, v91, v113
	v_add_f32_e32 v126, v122, v111
	ds_read_b128 v[110:113], v100 offset:13312
	s_waitcnt lgkmcnt(1)
	v_mul_f32_e32 v115, v89, v115
	v_fmac_f32_e32 v115, v88, v114
	v_fmac_f32_e32 v115, v90, v116
	v_fmac_f32_e32 v115, v91, v117
	v_add_f32_e32 v127, v123, v115
	ds_read_b128 v[114:117], v100 offset:17408
	s_waitcnt lgkmcnt(1)
	v_mul_f32_e32 v111, v89, v111
	v_fmac_f32_e32 v111, v88, v110
	v_fmac_f32_e32 v111, v90, v112
	v_fmac_f32_e32 v111, v91, v113
	v_add_f32_e32 v99, v99, v111
	ds_read_b128 v[110:113], v100 offset:21504
	s_waitcnt lgkmcnt(1)
	v_mul_f32_e32 v115, v89, v115
	v_fmac_f32_e32 v115, v88, v114
	v_fmac_f32_e32 v115, v90, v116
	v_fmac_f32_e32 v115, v91, v117
	v_add_f32_e32 v128, v96, v115
	ds_read_b128 v[114:117], v100 offset:25600
	s_waitcnt lgkmcnt(1)
	v_mul_f32_e32 v96, v89, v111
	v_fmac_f32_e32 v96, v88, v110
	v_fmac_f32_e32 v96, v90, v112
	v_fmac_f32_e32 v96, v91, v113
	ds_read_b128 v[110:113], v100 offset:29696
	v_add_f32_e32 v129, v95, v96
	s_waitcnt lgkmcnt(1)
	v_mul_f32_e32 v95, v89, v115
	v_fmac_f32_e32 v95, v88, v114
	v_fmac_f32_e32 v95, v90, v116
	v_fmac_f32_e32 v95, v91, v117
	v_add_f32_e32 v130, v94, v95
	s_waitcnt lgkmcnt(0)
	v_mul_f32_e32 v94, v89, v111
	v_fmac_f32_e32 v94, v88, v110
	v_fmac_f32_e32 v94, v90, v112
	v_fmac_f32_e32 v94, v91, v113
	ds_read_b128 v[110:113], v100 offset:38912
	ds_read_b128 v[114:117], v98 offset:2048
	ds_read_b128 v[118:121], v93 offset:2048
	ds_read_b128 v[122:125], v100 offset:2048
	v_add_f32_e32 v131, v97, v94
	v_pk_mul_f32 v[94:95], v[26:27], v[92:93] op_sel_hi:[1,0]
	s_waitcnt lgkmcnt(2)
	v_pk_add_f32 v[96:97], v[114:115], 1.0 op_sel_hi:[1,0]
	v_pk_mul_f32 v[94:95], v[94:95], v[110:111]
	v_pk_add_f32 v[110:111], v[116:117], 1.0 op_sel_hi:[1,0]
	s_waitcnt lgkmcnt(1)
	v_pk_fma_f32 v[94:95], v[94:95], v[96:97], v[118:119]
	v_pk_mul_f32 v[96:97], v[28:29], v[92:93] op_sel_hi:[1,0]
	s_nop 0
	v_pk_mul_f32 v[96:97], v[96:97], v[112:113]
	s_nop 0
	v_pk_fma_f32 v[96:97], v[96:97], v[110:111], v[120:121]
	ds_read_b128 v[110:113], v100 offset:6144
	s_waitcnt lgkmcnt(1)
	v_mul_f32_e32 v114, v95, v123
	v_fmac_f32_e32 v114, v94, v122
	v_fmac_f32_e32 v114, v96, v124
	v_fmac_f32_e32 v114, v97, v125
	v_add_f32_e32 v132, v109, v114
	ds_read_b128 v[114:117], v100 offset:10240
	s_waitcnt lgkmcnt(1)
	v_mul_f32_e32 v109, v95, v111
	v_fmac_f32_e32 v109, v94, v110
	v_fmac_f32_e32 v109, v96, v112
	v_fmac_f32_e32 v109, v97, v113
	ds_read_b128 v[110:113], v100 offset:14336
	v_add_f32_e32 v133, v126, v109
	s_waitcnt lgkmcnt(1)
	v_mul_f32_e32 v109, v95, v115
	v_fmac_f32_e32 v109, v94, v114
	v_fmac_f32_e32 v109, v96, v116
	v_fmac_f32_e32 v109, v97, v117
	ds_read_b128 v[114:117], v100 offset:18432
	ds_read_b128 v[118:121], v100 offset:22528
	v_add_f32_e32 v134, v127, v109
	s_waitcnt lgkmcnt(2)
	v_mul_f32_e32 v109, v95, v111
	v_fmac_f32_e32 v109, v94, v110
	v_fmac_f32_e32 v109, v96, v112
	v_fmac_f32_e32 v109, v97, v113
	v_add_f32_e32 v113, v99, v109
	s_waitcnt lgkmcnt(1)
	v_mul_f32_e32 v99, v95, v115
	v_fmac_f32_e32 v99, v94, v114
	v_fmac_f32_e32 v99, v96, v116
	v_fmac_f32_e32 v99, v97, v117
	ds_read_b128 v[114:117], v100 offset:26624
	v_add_f32_e32 v111, v128, v99
	s_waitcnt lgkmcnt(1)
	v_mul_f32_e32 v99, v95, v119
	v_fmac_f32_e32 v99, v94, v118
	v_fmac_f32_e32 v99, v96, v120
	v_fmac_f32_e32 v99, v97, v121
	ds_read_b128 v[118:121], v100 offset:30720
	v_add_f32_e32 v110, v129, v99
	s_waitcnt lgkmcnt(1)
	v_mul_f32_e32 v99, v95, v115
	v_fmac_f32_e32 v99, v94, v114
	v_fmac_f32_e32 v99, v96, v116
	v_fmac_f32_e32 v99, v97, v117
	v_add_f32_e32 v109, v130, v99
	s_waitcnt lgkmcnt(0)
	v_mul_f32_e32 v99, v95, v119
	v_fmac_f32_e32 v99, v94, v118
	v_fmac_f32_e32 v99, v96, v120
	v_fmac_f32_e32 v99, v97, v121
	ds_read_b128 v[114:117], v100 offset:39936
	ds_read_b128 v[118:121], v98 offset:3072
	ds_read_b128 v[122:125], v93 offset:3072
	v_add_f32_e32 v112, v131, v99
	v_pk_mul_f32 v[98:99], v[30:31], v[92:93] op_sel_hi:[1,0]
	v_pk_mul_f32 v[92:93], v[32:33], v[92:93] op_sel_hi:[1,0]
	s_waitcnt lgkmcnt(2)
	v_pk_mul_f32 v[98:99], v[98:99], v[114:115]
	s_waitcnt lgkmcnt(1)
	v_pk_add_f32 v[114:115], v[118:119], 1.0 op_sel_hi:[1,0]
	v_pk_mul_f32 v[92:93], v[92:93], v[116:117]
	s_waitcnt lgkmcnt(0)
	v_pk_fma_f32 v[98:99], v[98:99], v[114:115], v[122:123]
	v_pk_add_f32 v[114:115], v[120:121], 1.0 op_sel_hi:[1,0]
	ds_read_b128 v[126:129], v100 offset:3072
	v_pk_fma_f32 v[92:93], v[92:93], v[114:115], v[124:125]
	ds_read_b128 v[114:117], v100 offset:7168
	s_waitcnt lgkmcnt(1)
	v_mul_f32_e32 v118, v99, v127
	v_fmac_f32_e32 v118, v98, v126
	s_waitcnt lgkmcnt(0)
	v_mul_f32_e32 v115, v99, v115
	v_fmac_f32_e32 v115, v98, v114
	v_fmac_f32_e32 v118, v92, v128
	v_fmac_f32_e32 v115, v92, v116
	v_fmac_f32_e32 v118, v93, v129
	v_fmac_f32_e32 v115, v93, v117
	v_add_f32_e32 v122, v132, v118
	ds_read_b128 v[118:121], v100 offset:11264
	v_add_f32_e32 v123, v133, v115
	ds_read_b128 v[114:117], v100 offset:15360
	s_waitcnt lgkmcnt(1)
	v_mul_f32_e32 v119, v99, v119
	v_fmac_f32_e32 v119, v98, v118
	s_waitcnt lgkmcnt(0)
	v_mul_f32_e32 v115, v99, v115
	v_fmac_f32_e32 v115, v98, v114
	v_fmac_f32_e32 v119, v92, v120
	v_fmac_f32_e32 v115, v92, v116
	v_fmac_f32_e32 v119, v93, v121
	v_fmac_f32_e32 v115, v93, v117
	v_add_f32_e32 v124, v134, v119
	ds_read_b128 v[118:121], v100 offset:19456
	v_add_f32_e32 v113, v113, v115
	ds_read_b128 v[114:117], v100 offset:23552
	s_waitcnt lgkmcnt(1)
	v_mul_f32_e32 v119, v99, v119
	v_fmac_f32_e32 v119, v98, v118
	s_waitcnt lgkmcnt(0)
	v_mul_f32_e32 v115, v99, v115
	v_fmac_f32_e32 v115, v98, v114
	v_fmac_f32_e32 v119, v92, v120
	v_fmac_f32_e32 v115, v92, v116
	v_fmac_f32_e32 v119, v93, v121
	v_fmac_f32_e32 v115, v93, v117
	v_add_f32_e32 v111, v111, v119
	ds_read_b128 v[118:121], v100 offset:27648
	v_add_f32_e32 v110, v110, v115
	ds_read_b128 v[114:117], v100 offset:31744
	s_waitcnt lgkmcnt(1)
	v_mul_f32_e32 v119, v99, v119
	v_fmac_f32_e32 v119, v98, v118
	s_waitcnt lgkmcnt(0)
	v_mul_f32_e32 v115, v99, v115
	v_fmac_f32_e32 v115, v98, v114
	v_cndmask_b32_e64 v114, v122, v111, s[40:41]
	ds_bpermute_b32 v114, v249, v114
	v_fmac_f32_e32 v119, v92, v120
	v_fmac_f32_e32 v115, v92, v116
	v_fmac_f32_e32 v119, v93, v121
	v_fmac_f32_e32 v115, v93, v117
	v_add_f32_e32 v109, v109, v119
	v_add_f32_e32 v112, v112, v115
	v_cndmask_b32_e64 v111, v111, v122, s[40:41]
	s_waitcnt lgkmcnt(0)
	v_add_f32_e32 v111, v111, v114
	v_cndmask_b32_e64 v114, v110, v123, s[40:41]
	v_cndmask_b32_e64 v110, v123, v110, s[40:41]
	v_cndmask_b32_e64 v115, v124, v109, s[40:41]
	v_cndmask_b32_e64 v116, v113, v112, s[40:41]
	ds_bpermute_b32 v110, v249, v110
	ds_bpermute_b32 v115, v249, v115
	ds_bpermute_b32 v108, v249, v116
	v_cndmask_b32_e64 v109, v109, v124, s[40:41]
	v_cndmask_b32_e64 v112, v112, v113, s[40:41]
	s_waitcnt lgkmcnt(2)
	v_add_f32_e32 v110, v114, v110
	s_waitcnt lgkmcnt(1)
	v_add_f32_e32 v109, v109, v115
	s_waitcnt lgkmcnt(0)
	v_add_f32_e32 v108, v112, v108
	v_cndmask_b32_e64 v112, v111, v109, s[42:43]
	v_cndmask_b32_e64 v113, v110, v108, s[42:43]
	ds_bpermute_b32 v112, v248, v112
	ds_bpermute_b32 v107, v248, v113
	v_cndmask_b32_e64 v109, v109, v111, s[42:43]
	v_cndmask_b32_e64 v108, v108, v110, s[42:43]
	s_waitcnt lgkmcnt(1)
	v_add_f32_e32 v109, v109, v112
	s_waitcnt lgkmcnt(0)
	v_add_f32_e32 v107, v108, v107
	v_cndmask_b32_e64 v108, v109, v107, s[44:45]
	ds_bpermute_b32 v106, v247, v108
	v_cndmask_b32_e64 v87, v107, v109, s[44:45]
	s_waitcnt lgkmcnt(0)
	v_add_f32_e32 v108, v87, v106
	ds_bpermute_b32 v105, v246, v108
	v_cvt_pk_bf16_f32 v87, v84, v85
	v_cvt_pk_bf16_f32 v84, v88, v89
	v_lshl_add_u64 v[106:107], v[66:67], 0, s[2:3]
	v_cvt_pk_bf16_f32 v85, v90, v91
	s_waitcnt lgkmcnt(0)
	v_add_f32_e32 v88, v108, v105
	ds_bpermute_b32 v89, v245, v88
	global_store_dwordx2 v[106:107], v[84:85], off offset:512
	global_store_dwordx2 v[106:107], v[86:87], off
	v_cvt_pk_bf16_f32 v86, v94, v95
	v_cvt_pk_bf16_f32 v87, v96, v97
	s_waitcnt lgkmcnt(0)
	v_add_f32_e32 v84, v88, v89
	ds_bpermute_b32 v85, v244, v84
	global_store_dwordx2 v[106:107], v[86:87], off offset:1024
	v_cvt_pk_bf16_f32 v86, v98, v99
	v_cvt_pk_bf16_f32 v87, v92, v93
	global_store_dwordx2 v[106:107], v[86:87], off offset:1536
	s_and_saveexec_b64 s[18:19], s[46:47]
	s_cbranch_execz .LBB0_489
	s_lshl_b64 s[2:3], s[56:57], 5
	s_waitcnt lgkmcnt(0)
	v_add_f32_e32 v86, v84, v85
	v_lshl_add_u64 v[84:85], v[64:65], 0, s[2:3]
	global_store_dword v[84:85], v86, off

.LBB0_490:
	s_add_i32 s1, s59, s50
	s_cmp_lt_i32 s1, s26
	s_cselect_b32 s24, s1, s0
	s_cmpk_gt_i32 s24, 0x7fff
	s_mov_b64 s[28:29], -1
	s_cbranch_scc0 .LBB0_492
	s_add_i32 s26, s24, 0xffff8000
	s_lshl_b64 s[2:3], s[26:27], 12
	s_mov_b32 s1, s78
	s_add_u32 s18, s1, s2
	s_mov_b32 s1, s79
	s_mov_b32 s26, s80
	s_addc_u32 s19, s1, s3
	s_mov_b32 s25, s27
	s_mov_b64 s[28:29], 0

.LBB0_504:
	s_waitcnt vmcnt(6)
	v_lshlrev_b32_e32 v116, 16, v76
	v_and_b32_e32 v117, 0xffff0000, v76
	v_and_b32_e32 v113, 0xffff0000, v78
	v_lshlrev_b32_e32 v112, 16, v78
	v_lshlrev_b32_e32 v114, 16, v79
	v_and_b32_e32 v115, 0xffff0000, v79
	v_lshlrev_b32_e32 v118, 16, v77
	v_and_b32_e32 v119, 0xffff0000, v77
	v_mul_f32_e32 v78, v113, v113
	v_mul_f32_e32 v79, v117, v117
	s_waitcnt vmcnt(5)
	v_and_b32_e32 v121, 0xffff0000, v82
	v_fma_f32 v76, v112, v112, v78
	v_fma_f32 v77, v116, v116, v79
	s_waitcnt vmcnt(4)
	v_lshlrev_b32_e32 v124, 16, v80
	v_and_b32_e32 v125, 0xffff0000, v80
	v_lshlrev_b32_e32 v126, 16, v81
	v_and_b32_e32 v127, 0xffff0000, v81
	v_fma_f32 v76, v114, v114, v76
	v_fma_f32 v77, v118, v118, v77
	v_lshlrev_b32_e32 v120, 16, v82
	v_fma_f32 v76, v115, v115, v76
	v_fma_f32 v77, v119, v119, v77
	v_lshlrev_b32_e32 v122, 16, v83
	v_mul_f32_e32 v80, v121, v121
	v_mul_f32_e32 v81, v125, v125
	v_and_b32_e32 v123, 0xffff0000, v83
	v_fma_f32 v78, v120, v120, v80
	v_fma_f32 v79, v124, v124, v81
	v_fma_f32 v78, v122, v122, v78
	v_fma_f32 v79, v126, v126, v79
	v_add_f32_e32 v76, v76, v77
	v_fma_f32 v78, v123, v123, v78
	v_fma_f32 v79, v127, v127, v79
	v_add_f32_e32 v76, v76, v78
	v_add_f32_e32 v76, v76, v79
	ds_bpermute_b32 v77, v249, v76
	s_add_i32 s2, s52, 0xffff8000
	s_waitcnt lgkmcnt(0)
	v_add_f32_e32 v76, v76, v77
	ds_bpermute_b32 v77, v248, v76
	s_ashr_i32 s3, s52, 31
	s_mov_b32 s60, s83
	s_waitcnt lgkmcnt(0)
	v_add_f32_e32 v76, v76, v77
	ds_bpermute_b32 v77, v247, v76
	s_cmpk_gt_i32 s52, 0x7fff
	s_mov_b32 s61, s84
	s_waitcnt lgkmcnt(0)
	v_add_f32_e32 v76, v76, v77
	ds_bpermute_b32 v77, v246, v76
	s_mov_b32 s18, s85
	s_cselect_b32 s3, 0, s3
	s_waitcnt lgkmcnt(0)
	v_add_f32_e32 v76, v76, v77
	ds_bpermute_b32 v77, v245, v76
	s_cselect_b32 s2, s2, s52
	s_cselect_b32 s19, s18, s61
	s_waitcnt lgkmcnt(0)
	v_add_f32_e32 v92, v76, v77
	ds_bpermute_b32 v93, v244, v92
	s_mov_b32 s18, s86
	s_cselect_b32 s18, s18, s60
	s_lshl_b64 s[2:3], s[2:3], 12
	s_add_u32 s18, s18, s2
	s_addc_u32 s19, s19, s3
	s_and_b32 s2, s1, 0xfffff000
	s_waitcnt lgkmcnt(0)
	v_add_f32_e32 v92, v92, v93
	v_add_u32_e32 v103, s2, v100
	v_fmamk_f32 v92, v92, 0x3a800000, v218
	s_mov_b32 s2, 0x800000
	v_mul_f32_e32 v93, 0x4b800000, v92
	v_cmp_gt_f32_e32 vcc, s2, v92
	ds_read_b128 v[76:79], v100 offset:32768
	ds_read_b128 v[80:83], v100 offset:33792
	ds_read_b128 v[84:87], v103 offset:40960
	ds_read_b128 v[88:91], v103 offset:41984
	v_cndmask_b32_e32 v92, v92, v93, vcc
	v_rsq_f32_e32 v128, v92
	ds_read_b128 v[92:95], v100 offset:34816
	ds_read_b128 v[96:99], v100 offset:35840
	ds_read_b128 v[104:107], v103 offset:43008
	ds_read_b128 v[108:111], v103 offset:44032
	s_mov_b32 s62, s87
	s_mov_b32 s63, s88
	v_mul_f32_e32 v103, 0x45800000, v128
	v_cndmask_b32_e32 v128, v128, v103, vcc
	v_pk_mul_f32 v[112:113], v[128:129], v[112:113] op_sel_hi:[0,1]
	s_waitcnt lgkmcnt(7)
	v_pk_mul_f32 v[76:77], v[76:77], v[112:113]
	s_waitcnt lgkmcnt(5)
	v_pk_fma_f32 v[46:47], v[84:85], v[76:77], v[46:47]
	v_pk_mul_f32 v[76:77], v[128:129], v[114:115] op_sel_hi:[0,1]
	v_pk_mul_f32 v[76:77], v[78:79], v[76:77]
	s_nop 0
	v_pk_fma_f32 v[48:49], v[86:87], v[76:77], v[48:49]
	v_pk_mul_f32 v[76:77], v[128:129], v[116:117] op_sel_hi:[0,1]
	v_pk_mul_f32 v[76:77], v[80:81], v[76:77]
	global_store_dwordx4 v8, v[46:49], s[18:19] nt
	s_waitcnt lgkmcnt(4)
	v_pk_fma_f32 v[42:43], v[88:89], v[76:77], v[42:43]
	v_pk_mul_f32 v[76:77], v[128:129], v[118:119] op_sel_hi:[0,1]
	v_pk_mul_f32 v[76:77], v[82:83], v[76:77]
	s_nop 0
	v_pk_fma_f32 v[44:45], v[90:91], v[76:77], v[44:45]
	v_pk_mul_f32 v[76:77], v[128:129], v[120:121] op_sel_hi:[0,1]
	s_waitcnt lgkmcnt(3)
	v_pk_mul_f32 v[76:77], v[92:93], v[76:77]
	global_store_dwordx4 v8, v[42:45], s[18:19] offset:1024 nt
	s_waitcnt lgkmcnt(1)
	v_pk_fma_f32 v[38:39], v[104:105], v[76:77], v[38:39]
	v_pk_mul_f32 v[76:77], v[128:129], v[122:123] op_sel_hi:[0,1]
	v_pk_mul_f32 v[76:77], v[94:95], v[76:77]
	s_nop 0
	v_pk_fma_f32 v[40:41], v[106:107], v[76:77], v[40:41]
	v_pk_mul_f32 v[76:77], v[128:129], v[124:125] op_sel_hi:[0,1]
	v_pk_mul_f32 v[76:77], v[76:77], v[96:97]
	global_store_dwordx4 v8, v[38:41], s[18:19] offset:2048 nt
	s_waitcnt lgkmcnt(0)
	v_pk_fma_f32 v[34:35], v[108:109], v[76:77], v[34:35]
	v_pk_mul_f32 v[76:77], v[128:129], v[126:127] op_sel_hi:[0,1]
	v_pk_mul_f32 v[76:77], v[76:77], v[98:99]
	s_nop 0
	v_pk_fma_f32 v[36:37], v[110:111], v[76:77], v[36:37]
	global_store_dwordx4 v8, v[34:37], s[18:19] offset:3072 nt
	s_and_b64 vcc, exec, s[48:49]
	s_cbranch_vccnz .LBB0_451
.LBB0_505:
	s_waitcnt vmcnt(6)
	v_mul_f32_e32 v78, v43, v43
	v_mul_f32_e32 v79, v47, v47
	s_waitcnt vmcnt(4)
	v_fma_f32 v76, v42, v42, v78
	v_fma_f32 v77, v46, v46, v79
	v_fma_f32 v76, v44, v44, v76
	v_fma_f32 v77, v48, v48, v77
	v_fma_f32 v76, v45, v45, v76
	v_fma_f32 v77, v49, v49, v77
	v_mul_f32_e32 v80, v35, v35
	v_mul_f32_e32 v81, v39, v39
	v_add_f32_e32 v76, v76, v77
	v_fma_f32 v78, v34, v34, v80
	v_fma_f32 v79, v38, v38, v81
	v_fma_f32 v78, v36, v36, v78
	v_fma_f32 v79, v40, v40, v79
	v_fma_f32 v78, v37, v37, v78
	v_fma_f32 v79, v41, v41, v79
	v_and_b32_e32 v77, 64, v220
	v_add_f32_e32 v76, v79, v76
	v_add_f32_e32 v76, v78, v76
	v_add_u32_e32 v77, 64, v77
	s_mov_b32 s2, 0x800000
	s_and_b32 s1, s1, 0xfffff000
	ds_bpermute_b32 v78, v249, v76
	v_add_u32_e32 v84, s1, v101
	ds_read_b128 v[86:89], v100 offset:36864
	ds_read_b128 v[90:93], v84
	s_ashr_i32 s53, s52, 31
	s_waitcnt lgkmcnt(2)
	v_add_f32_e32 v76, v76, v78
	s_nop 1
	ds_bpermute_b32 v78, v248, v76
	s_waitcnt lgkmcnt(0)
	v_add_f32_e32 v76, v76, v78
	s_nop 1
	ds_bpermute_b32 v78, v247, v76
	s_waitcnt lgkmcnt(0)
	v_add_f32_e32 v76, v76, v78
	s_nop 1
	ds_bpermute_b32 v78, v246, v76
	s_waitcnt lgkmcnt(0)
	v_add_f32_e32 v76, v76, v78
	s_nop 1
	ds_bpermute_b32 v83, v245, v76
	s_waitcnt lgkmcnt(0)
	v_add_f32_e32 v76, v76, v83
	v_xor_b32_e32 v83, 1, v220
	v_cmp_lt_i32_e32 vcc, v83, v77
	s_nop 1
	v_cndmask_b32_e32 v77, v220, v83, vcc
	v_lshlrev_b32_e32 v77, 2, v77
	ds_bpermute_b32 v83, v244, v76
	s_waitcnt lgkmcnt(0)
	v_add_f32_e32 v76, v76, v83
	v_fmamk_f32 v76, v76, 0x3a800000, v218
	v_cmp_gt_f32_e32 vcc, s2, v76
	v_mul_f32_e32 v83, 0x4b800000, v76
	s_lshl_b64 s[2:3], s[52:53], 11
	v_cndmask_b32_e32 v76, v76, v83, vcc
	v_rsq_f32_e32 v76, v76
	s_nop 0
	v_mul_f32_e32 v83, 0x45800000, v76
	v_cndmask_b32_e32 v76, v76, v83, vcc
	v_add_u32_e32 v83, s1, v102
	ds_read_b128 v[94:97], v83
	v_pk_mul_f32 v[46:47], v[46:47], v[76:77] op_sel_hi:[1,0]
	v_pk_mul_f32 v[42:43], v[42:43], v[76:77] op_sel_hi:[1,0]
	v_pk_mul_f32 v[46:47], v[86:87], v[46:47]
	v_pk_add_f32 v[86:87], v[90:91], 1.0 op_sel_hi:[1,0]
	v_pk_mul_f32 v[44:45], v[44:45], v[76:77] op_sel_hi:[1,0]
	s_waitcnt lgkmcnt(0)
	v_pk_fma_f32 v[94:95], v[86:87], v[46:47], v[94:95]
	v_pk_mul_f32 v[46:47], v[48:49], v[76:77] op_sel_hi:[1,0]
	v_pk_add_f32 v[48:49], v[92:93], 1.0 op_sel_hi:[1,0]
	v_pk_mul_f32 v[46:47], v[88:89], v[46:47]
	ds_read_b128 v[86:89], v100
	v_pk_fma_f32 v[92:93], v[48:49], v[46:47], v[96:97]
	v_cvt_pk_bf16_f32 v48, v94, v95
	v_cvt_pk_bf16_f32 v49, v92, v93
	v_lshl_add_u64 v[46:47], v[66:67], 0, s[2:3]
	global_store_dwordx2 v[46:47], v[48:49], off
	s_waitcnt lgkmcnt(0)
	v_mul_f32_e32 v48, v87, v95
	v_fmac_f32_e32 v48, v86, v94
	v_fmac_f32_e32 v48, v88, v92
	v_fmac_f32_e32 v48, v89, v93
	ds_read_b128 v[86:89], v100 offset:4096
	v_add_f32_e32 v103, 0, v48
	v_pk_mul_f32 v[38:39], v[38:39], v[76:77] op_sel_hi:[1,0]
	v_pk_mul_f32 v[34:35], v[34:35], v[76:77] op_sel_hi:[1,0]
	v_pk_mul_f32 v[36:37], v[36:37], v[76:77] op_sel_hi:[1,0]
	s_waitcnt lgkmcnt(0)
	v_mul_f32_e32 v48, v87, v95
	v_fmac_f32_e32 v48, v86, v94
	v_fmac_f32_e32 v48, v88, v92
	v_fmac_f32_e32 v48, v89, v93
	ds_read_b128 v[86:89], v100 offset:8192
	v_add_f32_e32 v104, 0, v48
	s_waitcnt lgkmcnt(0)
	v_mul_f32_e32 v48, v87, v95
	v_fmac_f32_e32 v48, v86, v94
	v_fmac_f32_e32 v48, v88, v92
	v_fmac_f32_e32 v48, v89, v93
	ds_read_b128 v[86:89], v100 offset:12288
	v_add_f32_e32 v105, 0, v48
	s_waitcnt lgkmcnt(0)
	v_mul_f32_e32 v48, v87, v95
	v_fmac_f32_e32 v48, v86, v94
	v_fmac_f32_e32 v48, v88, v92
	v_fmac_f32_e32 v48, v89, v93
	ds_read_b128 v[88:91], v100 offset:16384
	v_add_f32_e32 v87, 0, v48
	s_waitcnt lgkmcnt(0)
	v_mul_f32_e32 v48, v89, v95
	v_fmac_f32_e32 v48, v88, v94
	v_fmac_f32_e32 v48, v90, v92
	v_fmac_f32_e32 v48, v91, v93
	ds_read_b128 v[88:91], v100 offset:20480
	v_add_f32_e32 v86, 0, v48
	s_waitcnt lgkmcnt(0)
	v_mul_f32_e32 v48, v89, v95
	v_fmac_f32_e32 v48, v88, v94
	v_fmac_f32_e32 v48, v90, v92
	v_fmac_f32_e32 v48, v91, v93
	ds_read_b128 v[88:91], v100 offset:24576
	v_add_f32_e32 v85, 0, v48
	s_waitcnt lgkmcnt(0)
	v_mul_f32_e32 v48, v89, v95
	v_fmac_f32_e32 v48, v88, v94
	v_fmac_f32_e32 v48, v90, v92
	v_fmac_f32_e32 v48, v91, v93
	ds_read_b128 v[88:91], v100 offset:28672
	v_add_f32_e32 v49, 0, v48
	s_waitcnt lgkmcnt(0)
	v_mul_f32_e32 v48, v95, v89
	v_fmac_f32_e32 v48, v94, v88
	v_fmac_f32_e32 v48, v92, v90
	v_fmac_f32_e32 v48, v93, v91
	ds_read_b128 v[88:91], v100 offset:37888
	ds_read_b128 v[92:95], v84 offset:1024
	ds_read_b128 v[96:99], v83 offset:1024
	v_add_f32_e32 v48, 0, v48
	s_waitcnt lgkmcnt(2)
	v_pk_mul_f32 v[42:43], v[42:43], v[88:89]
	s_waitcnt lgkmcnt(1)
	v_pk_add_f32 v[88:89], v[92:93], 1.0 op_sel_hi:[1,0]
	v_pk_mul_f32 v[44:45], v[44:45], v[90:91]
	s_waitcnt lgkmcnt(0)
	v_pk_fma_f32 v[42:43], v[42:43], v[88:89], v[96:97]
	v_pk_add_f32 v[88:89], v[94:95], 1.0 op_sel_hi:[1,0]
	s_nop 0
	v_pk_fma_f32 v[44:45], v[44:45], v[88:89], v[98:99]
	v_cvt_pk_bf16_f32 v88, v42, v43
	v_cvt_pk_bf16_f32 v89, v44, v45
	global_store_dwordx2 v[46:47], v[88:89], off offset:512
	ds_read_b128 v[88:91], v100 offset:1024
	s_waitcnt lgkmcnt(0)
	v_mul_f32_e32 v89, v43, v89
	v_fmac_f32_e32 v89, v42, v88
	v_fmac_f32_e32 v89, v44, v90
	v_fmac_f32_e32 v89, v45, v91
	ds_read_b128 v[90:93], v100 offset:5120
	v_add_f32_e32 v88, v103, v89
	s_waitcnt lgkmcnt(0)
	v_mul_f32_e32 v89, v43, v91
	v_fmac_f32_e32 v89, v42, v90
	v_fmac_f32_e32 v89, v44, v92
	v_fmac_f32_e32 v89, v45, v93
	ds_read_b128 v[90:93], v100 offset:9216
	v_add_f32_e32 v89, v104, v89
	s_waitcnt lgkmcnt(0)
	v_mul_f32_e32 v91, v43, v91
	v_fmac_f32_e32 v91, v42, v90
	v_fmac_f32_e32 v91, v44, v92
	v_fmac_f32_e32 v91, v45, v93
	v_add_f32_e32 v98, v105, v91
	ds_read_b128 v[90:93], v100 offset:13312
	s_waitcnt lgkmcnt(0)
	v_mul_f32_e32 v91, v43, v91
	v_fmac_f32_e32 v91, v42, v90
	v_fmac_f32_e32 v91, v44, v92
	v_fmac_f32_e32 v91, v45, v93
	v_add_f32_e32 v87, v87, v91
	ds_read_b128 v[90:93], v100 offset:17408
	s_waitcnt lgkmcnt(0)
	v_mul_f32_e32 v91, v43, v91
	v_fmac_f32_e32 v91, v42, v90
	v_fmac_f32_e32 v91, v44, v92
	v_fmac_f32_e32 v91, v45, v93
	v_add_f32_e32 v86, v86, v91
	ds_read_b128 v[90:93], v100 offset:21504
	s_waitcnt lgkmcnt(0)
	v_mul_f32_e32 v91, v43, v91
	v_fmac_f32_e32 v91, v42, v90
	v_fmac_f32_e32 v91, v44, v92
	v_fmac_f32_e32 v91, v45, v93
	v_add_f32_e32 v85, v85, v91
	ds_read_b128 v[90:93], v100 offset:25600
	s_waitcnt lgkmcnt(0)
	v_mul_f32_e32 v91, v43, v91
	v_fmac_f32_e32 v91, v42, v90
	v_fmac_f32_e32 v91, v44, v92
	v_fmac_f32_e32 v91, v45, v93
	v_add_f32_e32 v99, v49, v91
	ds_read_b128 v[90:93], v100 offset:29696
	s_waitcnt lgkmcnt(0)
	v_mul_f32_e32 v43, v43, v91
	v_fmac_f32_e32 v43, v42, v90
	v_fmac_f32_e32 v43, v44, v92
	v_fmac_f32_e32 v43, v45, v93
	v_add_f32_e32 v103, v48, v43
	ds_read_b128 v[42:45], v100 offset:38912
	ds_read_b128 v[90:93], v84 offset:2048
	ds_read_b128 v[94:97], v83 offset:2048
	s_waitcnt lgkmcnt(2)
	v_pk_mul_f32 v[38:39], v[38:39], v[42:43]
	s_waitcnt lgkmcnt(1)
	v_pk_add_f32 v[42:43], v[90:91], 1.0 op_sel_hi:[1,0]
	s_waitcnt lgkmcnt(0)
	v_pk_fma_f32 v[48:49], v[38:39], v[42:43], v[94:95]
	v_pk_mul_f32 v[38:39], v[40:41], v[76:77] op_sel_hi:[1,0]
	v_pk_add_f32 v[40:41], v[92:93], 1.0 op_sel_hi:[1,0]
	v_pk_mul_f32 v[38:39], v[38:39], v[44:45]
	s_nop 0
	v_pk_fma_f32 v[44:45], v[38:39], v[40:41], v[96:97]
	v_cvt_pk_bf16_f32 v38, v48, v49
	v_cvt_pk_bf16_f32 v39, v44, v45
	global_store_dwordx2 v[46:47], v[38:39], off offset:1024
	ds_read_b128 v[38:41], v100 offset:2048
	s_waitcnt lgkmcnt(0)
	v_mul_f32_e32 v39, v49, v39
	v_fmac_f32_e32 v39, v48, v38
	v_fmac_f32_e32 v39, v44, v40
	v_fmac_f32_e32 v39, v45, v41
	v_add_f32_e32 v43, v88, v39
	ds_read_b128 v[38:41], v100 offset:6144
	s_waitcnt lgkmcnt(0)
	v_mul_f32_e32 v39, v49, v39
	v_fmac_f32_e32 v39, v48, v38
	v_fmac_f32_e32 v39, v44, v40
	v_fmac_f32_e32 v39, v45, v41
	v_add_f32_e32 v104, v89, v39
	ds_read_b128 v[38:41], v100 offset:10240
	s_waitcnt lgkmcnt(0)
	v_mul_f32_e32 v39, v49, v39
	v_fmac_f32_e32 v39, v48, v38
	v_fmac_f32_e32 v39, v44, v40
	v_fmac_f32_e32 v39, v45, v41
	v_add_f32_e32 v98, v98, v39
	ds_read_b128 v[38:41], v100 offset:14336
	s_waitcnt lgkmcnt(0)
	v_mul_f32_e32 v39, v49, v39
	v_fmac_f32_e32 v39, v48, v38
	v_fmac_f32_e32 v39, v44, v40
	v_fmac_f32_e32 v39, v45, v41
	v_add_f32_e32 v42, v87, v39
	ds_read_b128 v[38:41], v100 offset:18432
	s_waitcnt lgkmcnt(0)
	v_mul_f32_e32 v39, v49, v39
	v_fmac_f32_e32 v39, v48, v38
	v_fmac_f32_e32 v39, v44, v40
	v_fmac_f32_e32 v39, v45, v41
	v_add_f32_e32 v41, v86, v39
	ds_read_b128 v[86:89], v100 offset:22528
	s_waitcnt lgkmcnt(0)
	v_mul_f32_e32 v38, v49, v87
	v_fmac_f32_e32 v38, v48, v86
	v_fmac_f32_e32 v38, v44, v88
	v_fmac_f32_e32 v38, v45, v89
	ds_read_b128 v[86:89], v100 offset:26624
	v_add_f32_e32 v40, v85, v38
	s_waitcnt lgkmcnt(0)
	v_mul_f32_e32 v38, v49, v87
	v_fmac_f32_e32 v38, v48, v86
	v_fmac_f32_e32 v38, v44, v88
	v_fmac_f32_e32 v38, v45, v89
	ds_read_b128 v[86:89], v100 offset:30720
	v_add_f32_e32 v39, v99, v38
	s_waitcnt lgkmcnt(0)
	v_mul_f32_e32 v38, v49, v87
	v_fmac_f32_e32 v38, v48, v86
	v_fmac_f32_e32 v38, v44, v88
	v_fmac_f32_e32 v38, v45, v89
	ds_read_b128 v[86:89], v100 offset:39936
	ds_read_b128 v[90:93], v84 offset:3072
	ds_read_b128 v[94:97], v83 offset:3072
	v_add_f32_e32 v38, v103, v38
	s_waitcnt lgkmcnt(2)
	v_pk_mul_f32 v[34:35], v[34:35], v[86:87]
	s_waitcnt lgkmcnt(1)
	v_pk_add_f32 v[44:45], v[90:91], 1.0 op_sel_hi:[1,0]
	v_pk_mul_f32 v[36:37], v[36:37], v[88:89]
	s_waitcnt lgkmcnt(0)
	v_pk_fma_f32 v[34:35], v[34:35], v[44:45], v[94:95]
	v_pk_add_f32 v[44:45], v[92:93], 1.0 op_sel_hi:[1,0]
	s_nop 0
	v_pk_fma_f32 v[36:37], v[36:37], v[44:45], v[96:97]
	v_cvt_pk_bf16_f32 v44, v34, v35
	v_cvt_pk_bf16_f32 v45, v36, v37
	global_store_dwordx2 v[46:47], v[44:45], off offset:1536
	ds_read_b128 v[44:47], v100 offset:3072
	s_waitcnt lgkmcnt(0)
	v_mul_f32_e32 v45, v35, v45
	v_fmac_f32_e32 v45, v34, v44
	v_fmac_f32_e32 v45, v36, v46
	v_fmac_f32_e32 v45, v37, v47
	v_add_f32_e32 v43, v43, v45
	ds_read_b128 v[44:47], v100 offset:7168
	s_waitcnt lgkmcnt(0)
	v_mul_f32_e32 v45, v35, v45
	v_fmac_f32_e32 v45, v34, v44
	v_fmac_f32_e32 v45, v36, v46
	v_fmac_f32_e32 v45, v37, v47
	v_add_f32_e32 v48, v104, v45
	ds_read_b128 v[44:47], v100 offset:11264
	s_waitcnt lgkmcnt(0)
	v_mul_f32_e32 v45, v35, v45
	v_fmac_f32_e32 v45, v34, v44
	v_fmac_f32_e32 v45, v36, v46
	v_fmac_f32_e32 v45, v37, v47
	v_add_f32_e32 v49, v98, v45
	ds_read_b128 v[44:47], v100 offset:15360
	s_waitcnt lgkmcnt(0)
	v_mul_f32_e32 v45, v35, v45
	v_fmac_f32_e32 v45, v34, v44
	v_fmac_f32_e32 v45, v36, v46
	v_fmac_f32_e32 v45, v37, v47
	v_add_f32_e32 v42, v42, v45
	ds_read_b128 v[44:47], v100 offset:19456
	s_waitcnt lgkmcnt(0)
	v_mul_f32_e32 v45, v35, v45
	v_fmac_f32_e32 v45, v34, v44
	v_fmac_f32_e32 v45, v36, v46
	v_fmac_f32_e32 v45, v37, v47
	v_add_f32_e32 v41, v41, v45
	ds_read_b128 v[44:47], v100 offset:23552
	s_waitcnt lgkmcnt(0)
	v_mul_f32_e32 v45, v35, v45
	v_fmac_f32_e32 v45, v34, v44
	v_fmac_f32_e32 v45, v36, v46
	v_fmac_f32_e32 v45, v37, v47
	v_add_f32_e32 v40, v40, v45
	ds_read_b128 v[44:47], v100 offset:27648
	s_waitcnt lgkmcnt(0)
	v_mul_f32_e32 v45, v35, v45
	v_fmac_f32_e32 v45, v34, v44
	v_fmac_f32_e32 v45, v36, v46
	v_fmac_f32_e32 v45, v37, v47
	v_add_f32_e32 v39, v39, v45
	ds_read_b128 v[44:47], v100 offset:31744
	s_waitcnt lgkmcnt(0)
	v_mul_f32_e32 v35, v35, v45
	v_fmac_f32_e32 v35, v34, v44
	v_fmac_f32_e32 v35, v36, v46
	v_cndmask_b32_e64 v36, v43, v41, s[40:41]
	v_fmac_f32_e32 v35, v37, v47
	ds_bpermute_b32 v36, v249, v36
	v_cndmask_b32_e64 v37, v48, v40, s[40:41]
	v_add_f32_e32 v34, v38, v35
	ds_bpermute_b32 v37, v249, v37
	v_cndmask_b32_e64 v38, v49, v39, s[40:41]
	ds_bpermute_b32 v38, v249, v38
	v_cndmask_b32_e64 v35, v41, v43, s[40:41]
	s_waitcnt lgkmcnt(2)
	v_add_f32_e32 v35, v35, v36
	v_cndmask_b32_e64 v36, v40, v48, s[40:41]
	s_waitcnt lgkmcnt(1)
	v_add_f32_e32 v36, v36, v37
	v_cndmask_b32_e64 v37, v39, v49, s[40:41]
	s_waitcnt lgkmcnt(0)
	v_add_f32_e32 v37, v37, v38
	v_cndmask_b32_e64 v38, v34, v42, s[40:41]
	v_cndmask_b32_e64 v34, v42, v34, s[40:41]
	ds_bpermute_b32 v34, v249, v34
	s_waitcnt lgkmcnt(0)
	v_add_f32_e32 v34, v38, v34
	v_cndmask_b32_e64 v38, v37, v35, s[42:43]
	v_cndmask_b32_e64 v35, v35, v37, s[42:43]
	v_cndmask_b32_e64 v37, v34, v36, s[42:43]
	v_cndmask_b32_e64 v34, v36, v34, s[42:43]
	ds_bpermute_b32 v35, v248, v35
	ds_bpermute_b32 v34, v248, v34
	s_waitcnt lgkmcnt(1)
	v_add_f32_e32 v35, v38, v35
	s_waitcnt lgkmcnt(0)
	v_add_f32_e32 v34, v37, v34
	v_cndmask_b32_e64 v36, v34, v35, s[44:45]
	v_cndmask_b32_e64 v34, v35, v34, s[44:45]
	ds_bpermute_b32 v34, v247, v34
	s_waitcnt lgkmcnt(0)
	v_add_f32_e32 v34, v36, v34
	ds_bpermute_b32 v35, v246, v34
	s_waitcnt lgkmcnt(0)
	v_add_f32_e32 v34, v34, v35
	ds_bpermute_b32 v35, v245, v34
	s_waitcnt lgkmcnt(0)
	v_add_f32_e32 v34, v34, v35
	ds_bpermute_b32 v35, v244, v34
	s_and_saveexec_b64 s[18:19], s[46:47]
	s_cbranch_execz .LBB0_450
	s_lshl_b64 s[2:3], s[52:53], 5
	s_waitcnt lgkmcnt(0)
	v_add_f32_e32 v36, v34, v35
	v_lshl_add_u64 v[34:35], v[64:65], 0, s[2:3]
	global_store_dword v[34:35], v36, off
	s_branch .LBB0_450
